# P12 final epilogue xb loads ring-prefetched; RS_TABLE rsqrt table finished after the first GEMM tile loads are issued (4 phases)
# speedup vs baseline: 1.0033x; 1.0021x over previous
; #define RS_TABLE(pm0_, ssq_) do { if (tid < 256) ((LAS float*)(lds + 131072))[tid] = rsqrtf((ssq_)[(pm0_) * 256 + tid] * (1.0f / D) + EPS); __syncthreads(); } while (0)
; __global__ void __launch_bounds__(512, 2) mk_fwd(Args a) {
;     ...
;         { pg8::Gemm g{XB, W1GU, T, 2 * FF, D}; pg8::StaticOrder S; S.init(T, 2 * FF, G, bid); RS_TABLE(PM_EVEN, SSQ0);
.LBB0_353:
	s_mov_b64 s[20:21], s[72:73]
	v_writelane_b32 v254, s64, 35
	s_mov_b64 s[22:23], s[74:75]
	s_mov_b64 s[24:25], s[76:77]
	s_mov_b64 s[26:27], s[78:79]
	s_mov_b64 s[28:29], s[80:81]
	s_mov_b64 s[30:31], s[82:83]
	s_mov_b64 s[16:17], s[68:69]
	v_writelane_b32 v254, s16, 36
	s_cmp_lt_i32 s88, 2
	s_cselect_b64 s[2:3], -1, 0
	v_writelane_b32 v254, s17, 37
	v_writelane_b32 v254, s18, 38
	v_writelane_b32 v254, s19, 39
	v_writelane_b32 v254, s20, 40
	v_writelane_b32 v254, s21, 41
	v_writelane_b32 v254, s22, 42
	v_writelane_b32 v254, s23, 43
	v_writelane_b32 v254, s24, 44
	s_add_u32 s96, s84, 0x600000
	v_writelane_b32 v254, s25, 45
	s_addc_u32 s97, s85, 0
	v_writelane_b32 v254, s26, 46
	s_add_u32 s10, s84, 0x800000
	v_writelane_b32 v254, s27, 47
	s_addc_u32 s11, s85, 0
	v_writelane_b32 v254, s28, 48
	s_add_u32 s94, s84, 0x11100000
	v_writelane_b32 v254, s29, 49
	s_addc_u32 s95, s85, 0
	s_and_b64 s[0:1], s[2:3], s[0:1]
	v_writelane_b32 v254, s30, 50
	s_andn2_b64 vcc, exec, s[0:1]
	v_writelane_b32 v254, s31, 51
	s_cbranch_vccnz .LBB0_520
	s_movk_i32 s0, 0x100
	v_cmp_gt_u32_e32 vcc, s0, v1
	s_and_saveexec_b64 s[0:1], vcc
	s_cbranch_execz .LBB0_356
	s_lshl_b32 s4, s87, 2
	s_and_b32 s4, s4, 24
	s_bfe_u32 s5, s87, 0x30003
	s_or_b32 s4, s4, s5
	v_lshlrev_b32_e32 v2, 2, v1
	v_lshl_or_b32 v3, s4, 10, v2
	global_load_dword v250, v3, s[84:85]

; #define PG8_STAGE(bufoff, gbase, voff) do { _Pragma("unroll") for (int _i = 0; _i < 2; ++_i) \
;         __builtin_amdgcn_global_load_lds((const unsigned*)((const char*)(gbase) + (voff)[_i]), (PG8_LAS unsigned*)(lds + (bufoff) + ldsw + _i * 8192), 16, 0, 0); } while (0)
; #define PG8_STAGEB(bufoff, gbase, voff) do { _Pragma("unroll") for (int _i = 0; _i < 2; ++_i) \
;         __builtin_amdgcn_global_load_lds((const unsigned*)((const char*)(gbase) + (voff)[_i]), (PG8_LAS unsigned*)(lds + (bufoff) + ldsw + _i * 8192), 16, 0, PG8_BAUX); } while (0)
; #define PG8_WAIT_V(n) asm volatile("s_waitcnt vmcnt(" #n ")" ::: "memory")
; #define PG8_BAR __builtin_amdgcn_s_barrier()
; template <class Epi, class Sched, bool ALIGN_EPI = false, bool SP2 = false>
; __device__ __forceinline__ void gemm_phase(PG8_LAS unsigned char* lds, const Gemm g, const Sched& S, const Epi& E) {
;     ...
;         PG8_STAGEB(PG8_SB(0, 0), cB, voffB); PG8_STAGEB(PG8_SB(0, 1), cB + hstep, voffB); PG8_STAGE(PG8_SA(0, 0), cA, voffA); PG8_STAGE(PG8_SA(0, 1), cA + hstep, voffA);
;         if (wr == 1) PG8_BAR;
;         PG8_WAIT_V(2); PG8_BAR;
;         PG8_STAGEB(PG8_SB(1, 0), cB + kstep, voffB); PG8_STAGE(PG8_SA(1, 0), cA + kstep, voffA); PG8_STAGEB(PG8_SB(1, 1), cB + hstep + kstep, voffB);
.LBB0_359:
	s_lshl_b32 s14, s14, 5
	s_and_b32 s20, s14, 0x60
	s_mov_b64 s[14:15], 0x80
	s_add_i32 m0, s40, 0x18000
	v_lshl_add_u64 v[8:9], v[8:9], 0, s[14:15]
	s_lshl_b32 s19, s18, 13
	s_waitcnt vmcnt(2)
	s_movk_i32 s98, 0x100
	v_cmp_gt_u32_e64 s[100:101], s98, v1
	s_nop 1
	s_and_saveexec_b64 s[100:101], s[100:101]
	s_cbranch_execz .Lrs_done_0
	v_mov_b32_e32 v252, 0x358637bd
	v_mov_b32_e32 v253, 0x800000
	v_fmac_f32_e32 v252, 0x3a000000, v250
	v_lshlrev_b32_e32 v251, 2, v1
	v_mul_f32_e32 v250, 0x4b800000, v252
	v_cmp_gt_f32_e64 s[98:99], v253, v252
	v_add_u32_e32 v251, 0x20000, v251
	s_nop 1
	v_cndmask_b32_e64 v250, v252, v250, s[98:99]
	v_rsq_f32_e32 v250, v250
	s_nop 0
	v_mul_f32_e32 v252, 0x45800000, v250
	v_cndmask_b32_e64 v250, v250, v252, s[98:99]
	ds_write_b32 v251, v250
.Lrs_done_0:
	s_or_b64 exec, exec, s[100:101]
	s_waitcnt lgkmcnt(0)
	s_barrier
	global_load_lds_dwordx4 v[8:9], off
	v_lshl_add_u64 v[6:7], v[6:7], 0, s[14:15]
	s_add_i32 m0, s40, 0x1a000
	s_add_i32 s45, s40, 0x8000
	s_add_i32 s46, s40, 0xa000
	global_load_lds_dwordx4 v[6:7], off
	v_lshl_add_u64 v[2:3], v[2:3], 0, s[14:15]
	s_mov_b32 m0, s45
	s_add_u32 s16, s30, 0x80080
	global_load_lds_dwordx4 v[2:3], off
	v_lshl_add_u64 v[2:3], v[4:5], 0, s[14:15]
	s_mov_b32 m0, s46
	s_addc_u32 s17, s31, 0
	global_load_lds_dwordx4 v[2:3], off
	s_add_i32 m0, s40, 0x1c000
	v_lshl_add_u64 v[2:3], s[16:17], 0, v[132:133]
	global_load_lds_dwordx4 v[2:3], off
	v_lshl_add_u64 v[2:3], s[16:17], 0, v[136:137]
	s_add_i32 m0, s40, 0x1e000
	s_cmpk_lt_u32 s1, 0x100
	global_load_lds_dwordx4 v[2:3], off
	s_sext_i32_i16 s27, s0
	s_cselect_b64 s[16:17], -1, 0
	s_lshl_b32 s0, s18, 8
	v_lshlrev_b32_e32 v3, 2, v152
	s_add_i32 s0, s0, 0x20000
	v_lshl_or_b32 v2, v152, 6, v151
	v_and_b32_e32 v4, 32, v3
	v_or_b32_e32 v156, s0, v3
	v_lshlrev_b32_e32 v3, 9, v1
	v_bitop3_b32 v2, v2, s19, v4 bitop3:0xde
	v_and_b32_e32 v3, 0x70000, v3
	v_lshlrev_b32_e32 v4, 12, v148
	v_or3_b32 v3, v146, v3, v4
	v_add_u32_e32 v138, v3, v147
	v_lshlrev_b32_e32 v3, 5, v149
	s_waitcnt vmcnt(6)
	v_and_b32_e32 v3, 0xf0000, v3
	v_lshl_or_b32 v155, s20, 7, v153
	v_or3_b32 v3, v146, v3, v4
	s_add_i32 s48, 0, 0x10000
	s_add_i32 s49, 0, 0x14000
	v_lshl_or_b32 v154, s18, 6, v152
	s_ashr_i32 s47, s86, 31
	v_or_b32_e32 v157, s20, v150
	v_mov_b32_e32 v139, v133
	v_add_u32_e32 v140, v3, v147
	v_mov_b32_e32 v141, v133
	v_mov_b64_e32 v[142:143], 0x580
	v_mov_b64_e32 v[144:145], 0x57f
	v_add_u32_e32 v158, s48, v155
	v_add_u32_e32 v159, s49, v155
	v_add_u32_e32 v160, 0, v2
	s_movk_i32 s50, 0x2c00
	s_barrier
	s_branch .LBB0_362

;     __device__ __forceinline__ bool next(int i, Unit& u) const { if (i != 0 || idx < 0 || idx >= 64) return false; const int h = idx >> 4, b = (idx >> 3) & 1; u.pm = h * 8 + (idx & 7); u.pn = b * 4 + h; return true; }
;     __device__ __forceinline__ bool next(int i, Unit& u) const { if (!b.next(i, u)) return false; u.pn += 8 * (u.pm >> 4); return true; }
;     __host__ __device__ bool next(int i, Unit& u) const {
;         const long L = (long)i * G + c; if (L >= nwg) return false;
;         int wgid = (int)L; { const int q = nwg / NXCD, r = nwg % NXCD, xcd = wgid % NXCD, off = wgid / NXCD; wgid = (xcd < r ? xcd * (q + 1) : r * (q + 1) + (xcd - r) * q) + off; }
;         const int nig = WGM * nN, gid = wgid / nig, fm = gid * WGM, gsz = (nM - fm) < WGM ? (nM - fm) : WGM;
;         u.pm = fm + ((wgid % nig) % gsz); u.pn = (wgid % nig) / gsz;
.LBB0_695:
	s_cmp_lt_i32 s88, 4
	s_cselect_b64 s[16:17], -1, 0
	s_add_u32 s2, s84, 0x13100000
	s_addc_u32 s3, s85, 0
	v_writelane_b32 v254, s2, 52
	s_nop 1
	v_writelane_b32 v254, s3, 53
	s_add_u32 s2, s84, 0x14100000
	s_addc_u32 s3, s85, 0
	s_add_u32 s12, s84, 0x16100000
	s_addc_u32 s13, s85, 0
	s_add_u32 s90, s84, 0x16300000
	v_writelane_b32 v254, s2, 54
	s_addc_u32 s91, s85, 0
	s_and_b64 s[0:1], s[16:17], s[0:1]
	v_writelane_b32 v254, s3, 55
	s_andn2_b64 vcc, exec, s[0:1]
	s_cbranch_vccnz .LBB0_956
	s_movk_i32 s0, 0x100
	v_cmp_gt_u32_e32 vcc, s0, v1
	s_and_saveexec_b64 s[0:1], vcc
	s_cbranch_execz .LBB0_698
	s_lshl_b32 s2, s87, 2
	s_lshr_b32 s4, s87, 3
	s_add_i32 s4, s4, s2
	s_and_b32 s3, s2, 24
	s_and_b32 s2, s4, 7
	s_or_b32 s2, s2, s3
	v_lshlrev_b32_e32 v2, 2, v1
	s_waitcnt lgkmcnt(0)
	v_lshl_or_b32 v3, s2, 10, v2
	global_load_dword v250, v3, s[18:19]
.LBB0_698:
	s_or_b64 exec, exec, s[0:1]
	s_cmpk_lt_i32 s87, 0x2a0
	s_cselect_b64 s[0:1], -1, 0
	s_cmpk_gt_i32 s87, 0x29f
	v_readfirstlane_b32 s18, v1
	s_waitcnt lgkmcnt(0)
	s_barrier
	s_cbranch_scc1 .LBB0_700
	s_ashr_i32 s2, s87, 31
	s_lshr_b32 s2, s2, 29
	s_add_i32 s2, s87, s2
	s_ashr_i32 s3, s2, 3
	s_and_b32 s2, s2, -8
	s_sub_i32 s2, s87, s2
	s_cmp_lt_i32 s2, 0
	s_movk_i32 s4, 0x55
	s_cselect_b32 s4, s4, 0x54
	s_mul_i32 s2, s2, s4
	s_add_i32 s2, s2, s3
	s_mul_hi_i32 s3, s2, 0x30c30c31
	s_lshr_b32 s4, s3, 31
	s_ashr_i32 s3, s3, 5
	s_add_i32 s3, s3, s4
	s_lshl_b32 s4, s3, 3
	s_mulk_i32 s3, 0xa8
	s_sub_i32 s2, s2, s3
	s_sext_i32_i16 s3, s2
	s_bfe_u32 s3, s3, 0x3001c
	s_add_i32 s3, s2, s3
	s_sext_i32_i16 s5, s3
	s_and_b32 s3, s3, 0xfff8
	s_sub_i32 s2, s2, s3
	s_sext_i32_i16 s2, s2
	s_add_i32 s2, s4, s2
	s_ashr_i32 s14, s5, 3

; #define PG8_STAGE(bufoff, gbase, voff) do { _Pragma("unroll") for (int _i = 0; _i < 2; ++_i) \
;         __builtin_amdgcn_global_load_lds((const unsigned*)((const char*)(gbase) + (voff)[_i]), (PG8_LAS unsigned*)(lds + (bufoff) + ldsw + _i * 8192), 16, 0, 0); } while (0)
; #define PG8_STAGEB(bufoff, gbase, voff) do { _Pragma("unroll") for (int _i = 0; _i < 2; ++_i) \
;         __builtin_amdgcn_global_load_lds((const unsigned*)((const char*)(gbase) + (voff)[_i]), (PG8_LAS unsigned*)(lds + (bufoff) + ldsw + _i * 8192), 16, 0, PG8_BAUX); } while (0)
; #define PG8_WAIT_V(n) asm volatile("s_waitcnt vmcnt(" #n ")" ::: "memory")
; #define PG8_BAR __builtin_amdgcn_s_barrier()
; template <class Epi, class Sched, bool ALIGN_EPI = false, bool SP2 = false>
; __device__ __forceinline__ void gemm_phase(PG8_LAS unsigned char* lds, const Gemm g, const Sched& S, const Epi& E) {
;     ...
;         PG8_STAGEB(PG8_SB(0, 0), cB, voffB); PG8_STAGEB(PG8_SB(0, 1), cB + hstep, voffB); PG8_STAGE(PG8_SA(0, 0), cA, voffA); PG8_STAGE(PG8_SA(0, 1), cA + hstep, voffA);
;         if (wr == 1) PG8_BAR;
;         PG8_WAIT_V(2); PG8_BAR;
;         PG8_STAGEB(PG8_SB(1, 0), cB + kstep, voffB); PG8_STAGE(PG8_SA(1, 0), cA + kstep, voffA); PG8_STAGEB(PG8_SB(1, 1), cB + hstep + kstep, voffB);
;         PG8_WAIT_V(6); PG8_BAR;
.LBB0_703:
	s_and_b32 s3, s0, 3
	s_lshl_b32 s15, s1, 6
	s_lshl_b32 s26, s1, 13
	s_lshl_b32 s67, s3, 5
	s_add_u32 s68, s84, 0x15100000
	s_mov_b64 s[22:23], 0x80
	s_addc_u32 s69, s85, 0
	s_add_i32 m0, s63, 0x18000
	v_lshl_add_u64 v[8:9], v[8:9], 0, s[22:23]
	s_waitcnt vmcnt(2)
	s_movk_i32 s98, 0x100
	v_cmp_gt_u32_e64 s[100:101], s98, v1
	s_nop 1
	s_and_saveexec_b64 s[100:101], s[100:101]
	s_cbranch_execz .Lrs_done_1
	v_mov_b32_e32 v252, 0x358637bd
	v_mov_b32_e32 v253, 0x800000
	v_fmac_f32_e32 v252, 0x3a000000, v250
	v_lshlrev_b32_e32 v251, 2, v1
	v_mul_f32_e32 v250, 0x4b800000, v252
	v_cmp_gt_f32_e64 s[98:99], v253, v252
	v_add_u32_e32 v251, 0x20000, v251
	s_nop 1
	v_cndmask_b32_e64 v250, v252, v250, s[98:99]
	v_rsq_f32_e32 v250, v250
	s_nop 0
	v_mul_f32_e32 v252, 0x45800000, v250
	v_cndmask_b32_e64 v250, v250, v252, s[98:99]
	ds_write_b32 v251, v250
.Lrs_done_1:
	s_or_b64 exec, exec, s[100:101]
	s_waitcnt lgkmcnt(0)
	s_barrier
	global_load_lds_dwordx4 v[8:9], off
	v_lshl_add_u64 v[6:7], v[6:7], 0, s[22:23]
	s_add_i32 m0, s63, 0x1a000
	s_add_i32 s70, s63, 0x8000
	s_add_i32 s71, s63, 0xa000
	global_load_lds_dwordx4 v[6:7], off
	v_lshl_add_u64 v[2:3], v[2:3], 0, s[22:23]
	s_mov_b32 m0, s70
	s_add_u32 s24, s50, 0x80080
	global_load_lds_dwordx4 v[2:3], off
	v_lshl_add_u64 v[2:3], v[4:5], 0, s[22:23]
	s_mov_b32 m0, s71
	s_addc_u32 s25, s51, 0
	global_load_lds_dwordx4 v[2:3], off
	s_add_i32 m0, s63, 0x1c000
	v_lshl_add_u64 v[2:3], s[24:25], 0, v[132:133]
	global_load_lds_dwordx4 v[2:3], off
	v_lshl_add_u64 v[2:3], s[24:25], 0, v[136:137]
	s_add_i32 m0, s63, 0x1e000
	s_cmpk_lt_u32 s18, 0x100
	global_load_lds_dwordx4 v[2:3], off
	v_lshlrev_b32_e32 v3, 2, v184
	v_lshl_or_b32 v2, v184, 6, v140
	v_and_b32_e32 v4, 32, v3
	v_bitop3_b32 v4, v2, s26, v4 bitop3:0xde
	s_cselect_b64 s[24:25], -1, 0
	s_lshl_b32 s1, s1, 8
	v_and_or_b32 v144, s67, 32, v138
	v_mov_b32_e32 v2, 0x4f
	v_lshlrev_b32_e32 v142, 2, v138
	s_add_i32 s1, s1, 0x20000
	v_bitop3_b32 v2, s15, v2, v184 bitop3:0xc8
	v_lshl_add_u64 v[146:147], s[6:7], 0, v[142:143]
	v_lshl_add_u64 v[148:149], s[8:9], 0, v[142:143]
	v_lshlrev_b32_e32 v142, 2, v144
	v_or_b32_e32 v194, s1, v3
	v_cvt_f32_ubyte0_e32 v195, v2
	v_lshl_add_u64 v[2:3], s[84:85], 0, v[142:143]
	s_mov_b64 s[6:7], 0x100000
	v_lshl_add_u64 v[150:151], v[2:3], 0, s[6:7]
	s_mov_b64 s[6:7], 0x200000
	v_lshl_add_u64 v[152:153], v[2:3], 0, s[6:7]
	v_lshlrev_b32_e32 v2, 9, v1
	s_cmp_lt_u32 s3, 2
	v_and_b32_e32 v2, 0x70000, v2
	v_lshlrev_b32_e32 v3, 12, v182
	s_cselect_b64 s[26:27], -1, 0
	s_lshl_b32 s72, s3, 6
	v_or3_b32 v2, v139, v2, v3
	s_or_b32 s73, s72, 0xfffff000
	s_bfe_u32 s74, s0, 0x10001
	s_ashr_i32 s75, s86, 31
	s_ashr_i32 s76, s87, 31
	v_add_u32_e32 v156, v2, v145
	v_lshlrev_b32_e32 v2, 5, v183
	s_waitcnt vmcnt(6)
	s_add_u32 s0, s90, s72
	v_and_b32_e32 v2, 0xf0000, v2
	v_lshl_or_b32 v193, s3, 12, v185
	s_addc_u32 s1, s91, 0
	v_mov_b32_e32 v141, v143
	v_or3_b32 v2, v139, v2, v3
	s_add_i32 s77, 0, 0x10000
	s_add_i32 s78, 0, 0x14000
	s_movk_i32 s28, 0xff80
	s_movk_i32 s30, 0xe800
	s_movk_i32 s34, 0xe900
	s_movk_i32 s38, 0xf000
	s_movk_i32 s40, 0xf100
	v_or_b32_e32 v192, s15, v184
	v_lshl_add_u64 v[154:155], s[0:1], 0, v[140:141]
	v_mov_b32_e32 v157, v143
	v_add_u32_e32 v158, v2, v145
	v_mov_b32_e32 v159, v143
	v_add_u32_e32 v141, s77, v193
	v_add_u32_e32 v196, s78, v193
	v_add_u32_e32 v197, 0, v4
	s_mov_b32 s79, 0xc2fc0000
	s_mov_b32 s29, -1
	s_mov_b32 s31, -1
	s_mov_b32 s35, -1
	s_mov_b32 s39, -1
	s_mov_b32 s41, -1
	v_mov_b32_e32 v198, 0x42800000
	v_mov_b32_e32 v199, 0x42000000
	v_mov_b32_e32 v200, 0x3e38aa3b
	v_not_b32_e32 v201, 63
	s_mov_b32 s80, 0
	s_barrier
	s_branch .LBB0_706

; #define RS_TABLE(pm0_, ssq_) do { if (tid < 256) ((LAS float*)(lds + 131072))[tid] = rsqrtf((ssq_)[(pm0_) * 256 + tid] * (1.0f / D) + EPS); __syncthreads(); } while (0)
; __global__ void __launch_bounds__(512, 2) mk_fwd(Args a) {
;     ...
;     if (IN(8)) { pg8::Gemm g{XB, WQ, T, D, D}; pg8::StaticOrder S; S.init(T, D, G, bid); RS_TABLE(PM_EVEN, SSQ2); EpiScale E{XQ, SSQ2, 0.04419417382415922f * LOG2E};
.LBB0_1417:
	s_cmp_lt_i32 s88, 9
	s_cselect_b64 s[4:5], -1, 0
	s_and_b64 s[2:3], s[4:5], s[2:3]
	s_andn2_b64 vcc, exec, s[2:3]
	s_cbranch_vccnz .LBB0_1444
	s_movk_i32 s2, 0x100
	v_cmp_gt_u32_e32 vcc, s2, v1
	s_and_saveexec_b64 s[2:3], vcc
	s_cbranch_execz .LBB0_1420
	s_lshl_b32 s8, s87, 2
	s_and_b32 s8, s8, 24
	s_bfe_u32 s9, s87, 0x30003
	s_or_b32 s8, s8, s9
	v_lshlrev_b32_e32 v2, 2, v1
	s_waitcnt lgkmcnt(0)
	v_lshl_or_b32 v3, s8, 10, v2
	global_load_dword v250, v3, s[6:7]
.LBB0_1420:
	s_or_b64 exec, exec, s[2:3]
	s_and_b64 vcc, exec, s[0:1]
	v_readfirstlane_b32 s10, v1
	s_waitcnt lgkmcnt(0)
	s_barrier
	s_cbranch_vccnz .LBB0_1444
	s_ashr_i32 s28, s87, 31
	s_lshr_b32 s2, s28, 29
	s_add_i32 s7, s87, s2
	s_and_b32 s2, s7, -8
	s_sub_i32 s8, s87, s2
	s_cmp_gt_i32 s8, -1
	s_cbranch_scc0 .LBB0_1423
	s_lshl_b32 s6, s8, 5
	s_cbranch_execz .LBB0_1424
	s_branch .LBB0_1425

; #define PG8_STAGE(bufoff, gbase, voff) do { _Pragma("unroll") for (int _i = 0; _i < 2; ++_i) \
;         __builtin_amdgcn_global_load_lds((const unsigned*)((const char*)(gbase) + (voff)[_i]), (PG8_LAS unsigned*)(lds + (bufoff) + ldsw + _i * 8192), 16, 0, 0); } while (0)
; #define PG8_STAGEB(bufoff, gbase, voff) do { _Pragma("unroll") for (int _i = 0; _i < 2; ++_i) \
;         __builtin_amdgcn_global_load_lds((const unsigned*)((const char*)(gbase) + (voff)[_i]), (PG8_LAS unsigned*)(lds + (bufoff) + ldsw + _i * 8192), 16, 0, PG8_BAUX); } while (0)
; #define PG8_WAIT_V(n) asm volatile("s_waitcnt vmcnt(" #n ")" ::: "memory")
; #define PG8_BAR __builtin_amdgcn_s_barrier()
; template <class Epi, class Sched, bool ALIGN_EPI = false, bool SP2 = false>
; __device__ __forceinline__ void gemm_phase(PG8_LAS unsigned char* lds, const Gemm g, const Sched& S, const Epi& E) {
;     ...
;         PG8_STAGEB(PG8_SB(0, 0), cB, voffB); PG8_STAGEB(PG8_SB(0, 1), cB + hstep, voffB); PG8_STAGE(PG8_SA(0, 0), cA, voffA); PG8_STAGE(PG8_SA(0, 1), cA + hstep, voffA);
;         if (wr == 1) PG8_BAR;
;         PG8_WAIT_V(2); PG8_BAR;
;         PG8_STAGEB(PG8_SB(1, 0), cB + kstep, voffB); PG8_STAGE(PG8_SA(1, 0), cA + kstep, voffA); PG8_STAGEB(PG8_SB(1, 1), cB + hstep + kstep, voffB);
;         PG8_WAIT_V(6); PG8_BAR;
.LBB0_1427:
	s_lshl_b32 s8, s8, 5
	s_and_b32 s14, s8, 0x60
	s_mov_b64 s[8:9], 0x80
	s_add_i32 m0, s17, 0x18000
	v_lshl_add_u64 v[8:9], v[8:9], 0, s[8:9]
	s_lshl_b32 s11, s3, 13
	s_lshl_b32 s15, s14, 7
	s_waitcnt vmcnt(2)
	s_movk_i32 s98, 0x100
	v_cmp_gt_u32_e64 s[100:101], s98, v1
	s_nop 1
	s_and_saveexec_b64 s[100:101], s[100:101]
	s_cbranch_execz .Lrs_done_2
	v_mov_b32_e32 v252, 0x358637bd
	v_mov_b32_e32 v253, 0x800000
	v_fmac_f32_e32 v252, 0x3a000000, v250
	v_lshlrev_b32_e32 v251, 2, v1
	v_mul_f32_e32 v250, 0x4b800000, v252
	v_cmp_gt_f32_e64 s[98:99], v253, v252
	v_add_u32_e32 v251, 0x20000, v251
	s_nop 1
	v_cndmask_b32_e64 v250, v252, v250, s[98:99]
	v_rsq_f32_e32 v250, v250
	s_nop 0
	v_mul_f32_e32 v252, 0x45800000, v250
	v_cndmask_b32_e64 v250, v250, v252, s[98:99]
	ds_write_b32 v251, v250
.Lrs_done_2:
	s_or_b64 exec, exec, s[100:101]
	s_waitcnt lgkmcnt(0)
	s_barrier
	global_load_lds_dwordx4 v[8:9], off
	v_lshl_add_u64 v[4:5], v[4:5], 0, s[8:9]
	s_add_i32 m0, s17, 0x1a000
	s_add_i32 s39, s17, 0x8000
	s_add_i32 s40, s17, 0xa000
	global_load_lds_dwordx4 v[4:5], off
	v_lshl_add_u64 v[2:3], v[2:3], 0, s[8:9]
	s_mov_b32 m0, s39
	s_add_u32 s12, s24, 0x80080
	global_load_lds_dwordx4 v[2:3], off
	v_lshl_add_u64 v[2:3], v[6:7], 0, s[8:9]
	s_mov_b32 m0, s40
	s_addc_u32 s13, s25, 0
	global_load_lds_dwordx4 v[2:3], off
	s_add_i32 m0, s17, 0x1c000
	v_lshl_add_u64 v[2:3], s[12:13], 0, v[132:133]
	global_load_lds_dwordx4 v[2:3], off
	v_lshl_add_u64 v[2:3], s[12:13], 0, v[136:137]
	s_add_i32 m0, s17, 0x1e000
	s_sext_i32_i8 s44, s2
	global_load_lds_dwordx4 v[2:3], off
	v_and_b32_e32 v2, 15, v1
	v_lshlrev_b32_e32 v3, 1, v13
	v_lshl_or_b32 v146, s3, 6, v2
	v_lshl_or_b32 v4, v2, 6, v3
	v_lshlrev_b32_e32 v2, 2, v2
	v_and_b32_e32 v5, 32, v2
	v_bitop3_b32 v4, v4, s11, v5 bitop3:0xde
	v_lshlrev_b32_e32 v5, 6, v1
	s_movk_i32 s2, 0x3c0
	s_cmpk_lt_u32 s10, 0x100
	v_and_or_b32 v3, v5, s2, v3
	s_cselect_b64 s[10:11], -1, 0
	s_lshl_b32 s2, s3, 8
	v_lshlrev_b32_e32 v5, 2, v1
	s_add_i32 s2, s2, 0x20000
	v_and_b32_e32 v5, 32, v5
	v_or_b32_e32 v148, s2, v2
	v_lshlrev_b32_e32 v2, 9, v1
	v_bitop3_b32 v147, s15, v3, v5 bitop3:0xf6
	v_and_b32_e32 v2, 0x70000, v2
	v_lshlrev_b32_e32 v3, 12, v12
	v_or3_b32 v2, v10, v2, v3
	v_add_u32_e32 v138, v2, v11
	v_lshlrev_b32_e32 v2, 5, v14
	s_waitcnt vmcnt(6)
	v_and_b32_e32 v2, 0xf0000, v2
	v_or3_b32 v2, v10, v2, v3
	s_add_i32 s42, 0, 0x10000
	s_add_i32 s43, 0, 0x14000
	s_ashr_i32 s41, s86, 31
	v_or_b32_e32 v149, s14, v13
	v_mov_b32_e32 v139, v133
	v_add_u32_e32 v140, v2, v11
	v_mov_b32_e32 v141, v133
	v_mov_b64_e32 v[142:143], 0x100
	v_mov_b64_e32 v[144:145], 0xff
	v_add_u32_e32 v152, s42, v147
	v_add_u32_e32 v153, s43, v147
	v_add_u32_e32 v154, 0, v4
	s_barrier
	s_branch .LBB0_1430

; #define PG8_LAS __attribute__((address_space(3)))
;     __host__ __device__ bool next(int i, Unit& u) const {
;         const long L = (long)i * G + c; if (L >= nwg) return false;
;         int wgid = (int)L; { const int q = nwg / NXCD, r = nwg % NXCD, xcd = wgid % NXCD, off = wgid / NXCD; wgid = (xcd < r ? xcd * (q + 1) : r * (q + 1) + (xcd - r) * q) + off; }
;         const int nig = WGM * nN, gid = wgid / nig, fm = gid * WGM, gsz = (nM - fm) < WGM ? (nM - fm) : WGM;
;         u.pm = fm + ((wgid % nig) % gsz); u.pn = (wgid % nig) / gsz;
;     ...
;         if (nM == 32 && (nN & 1) == 0 && nN >= 16 && nwg % NXCD == 0) { const int xcd = (int)(L % NXCD), half = nN / 2, base = (xcd & 1) * half; u.pn = base + (u.pn - base + (xcd >> 1) * (half / 4)) % half; }
;     ...
;         return true;
;     }
; template <class Epi, class Sched, bool ALIGN_EPI = false, bool SP2 = false>
; __device__ __forceinline__ void gemm_phase(PG8_LAS unsigned char* lds, const Gemm g, const Sched& S, const Epi& E) {
;     const int tid = threadIdx.x, wid = __builtin_amdgcn_readfirstlane(tid >> 6), lane = tid & 63, wr = wid >> 2, wc = wid & 3, fr = lane & 15, fq = lane >> 4;
;     const int K = g.K, nt = K / BK;
;     unsigned voffA[2], voffB[2];
; #pragma unroll
;     for (int i = 0; i < 2; ++i) { int R, C; stage_rc(tid * 16 + i * 8192, R, C); const int Rb = Epi::PERM ? ((R & ~31) + perm32(R & 31)) : R;
;         voffA[i] = (unsigned)(R * K + C) * 2u; voffB[i] = (unsigned)(Rb * K + C) * 2u; }
;     const size_t kstep = (size_t)(BK * 2);
;     const size_t hstep = (size_t)HALF * K * 2;
;     const size_t tstep = 2 * hstep;
;     const unsigned ldsw = (unsigned)wid * 1024u;
;     const int aoff = lds_byte(wr * 64 + fr, fq * 8), boff = lds_byte(wc * 32 + fr, fq * 8);
;     ...
;     Unit cur, nxt; int ui = 0;
;     if (!S.next(0, cur)) return;
;     f32x4 acc[2][2][4][2];
; #pragma unroll
;     for (int a = 0; a < 2; ++a)
; #pragma unroll
;         for (int b = 0; b < 2; ++b)
; #pragma unroll
;             for (int m = 0; m < 4; ++m)
; #pragma unroll
;                 for (int n = 0; n < 2; ++n) acc[a][b][m][n] = (f32x4){0.f, 0.f, 0.f, 0.f};
;     bf16x8 At[4][2], B0[2][2], B1[2][2];
;     const char* cA = (const char*)g.A + (size_t)cur.pm * tstep; const char* cB = (const char*)g.Bt + (size_t)cur.pn * tstep;
;     S.a_ready(cur);
;     if constexpr (SP2) {
.LBB0_1691:
	s_cmp_lt_i32 s88, 12
	s_cselect_b64 s[4:5], -1, 0
	s_and_b64 s[2:3], s[4:5], s[2:3]
	s_andn2_b64 vcc, exec, s[2:3]
	s_cbranch_vccnz .LBB0_1820
	s_movk_i32 s2, 0x100
	v_cmp_gt_u32_e32 vcc, s2, v1
	s_and_saveexec_b64 s[2:3], vcc
	s_cbranch_execz .LBB0_1694
	s_lshl_b32 s8, s87, 2
	s_and_b32 s8, s8, 24
	s_bfe_u32 s9, s87, 0x30003
	s_or_b32 s8, s8, s9
	v_lshlrev_b32_e32 v2, 2, v1
	s_waitcnt lgkmcnt(0)
	v_lshl_or_b32 v3, s8, 10, v2
	global_load_dword v250, v3, s[6:7]
.LBB0_1694:
	s_or_b64 exec, exec, s[2:3]
	s_cmpk_gt_i32 s87, 0x57f
	v_readfirstlane_b32 s3, v1
	s_waitcnt lgkmcnt(0)
	s_barrier
	s_cbranch_scc1 .LBB0_1710
	v_lshrrev_b32_e32 v2, 5, v1
	v_lshrrev_b32_e32 v4, 1, v1
	v_and_b32_e32 v2, 4, v2
	v_bfe_u32 v3, v1, 2, 2
	v_and_b32_e32 v13, 24, v4
	v_or3_b32 v2, v2, v3, v13
	v_lshlrev_b32_e32 v3, 4, v1
	v_add_u32_e32 v10, 0x2000, v3
	v_lshrrev_b32_e32 v4, 7, v10
	s_movk_i32 s2, 0xe0
	v_and_b32_e32 v6, 32, v1
	s_lshr_b32 s8, s3, 6
	v_and_or_b32 v5, v4, s2, v2
	v_bitop3_b32 v11, v3, v6, 48 bitop3:0x6c
	v_and_b32_e32 v12, 64, v1
	v_bfe_u32 v14, v1, 2, 4
	s_movk_i32 s2, 0xf0
	s_lshr_b32 s12, s3, 8
	s_lshl_b32 s28, s8, 10
	v_or_b32_e32 v3, v11, v12
	v_and_or_b32 v4, v4, s2, v14
	s_add_u32 s29, s84, 0x8f00000
	v_lshl_or_b32 v132, v4, 12, v3
	v_lshrrev_b32_e32 v4, 3, v1
	s_movk_i32 s2, 0x60
	s_addc_u32 s30, s85, 0
	v_and_or_b32 v2, v4, s2, v2
	s_movk_i32 s2, 0x70
	s_ashr_i32 s31, s87, 31
	v_lshl_or_b32 v134, v2, 12, v3
	v_and_or_b32 v2, v4, s2, v14
	s_lshr_b32 s2, s31, 29
	s_add_i32 s2, s87, s2
	s_ashr_i32 s6, s2, 3
	s_and_b32 s2, s2, -8
	s_sub_i32 s2, s87, s2
	s_cmp_lt_i32 s2, 0
	s_movk_i32 s33, 0xb1
	s_cselect_b32 s7, s33, 0xb0
	s_mul_i32 s2, s2, s7
	s_add_i32 s2, s2, s6
	s_mul_hi_i32 s6, s2, 0x2e8ba2e9
	s_lshr_b32 s7, s6, 31
	s_ashr_i32 s6, s6, 6
	s_add_i32 s6, s6, s7
	s_lshl_b32 s7, s6, 3
	s_mulk_i32 s6, 0x160
	s_sub_i32 s6, s2, s6
	s_sext_i32_i16 s2, s6
	s_bfe_u32 s2, s2, 0x3001c
	s_add_i32 s9, s6, s2
	s_sext_i32_i16 s2, s9
	s_and_b32 s9, s9, 0xfff8
	s_sub_i32 s6, s6, s9
	s_sext_i32_i16 s6, s6
	s_lshr_b32 s2, s2, 3
	s_add_i32 s20, s7, s6
	s_ashr_i32 s21, s20, 31
	s_bfe_i64 s[10:11], s[2:3], 0x100000
	s_lshl_b64 s[6:7], s[20:21], 20
	s_lshl_b64 s[10:11], s[10:11], 20
	s_add_u32 s24, s29, s10
	s_addc_u32 s25, s30, s11
	s_add_i32 s21, s28, 0
	s_add_i32 m0, s21, 0x10000
	v_lshl_or_b32 v130, v5, 12, v3
	global_load_lds_dwordx4 v134, s[24:25]
	s_add_i32 m0, s21, 0x12000
	s_add_u32 s10, s24, 0x80000
	global_load_lds_dwordx4 v130, s[24:25]
	s_addc_u32 s11, s25, 0
	s_add_i32 m0, s21, 0x14000
	v_lshl_or_b32 v136, v2, 12, v3
	global_load_lds_dwordx4 v134, s[10:11]
	s_add_i32 m0, s21, 0x16000
	s_add_u32 s22, s36, s6
	s_addc_u32 s23, s37, s7
	s_add_i32 s34, s21, 0x2000
	global_load_lds_dwordx4 v130, s[10:11]
	s_mov_b32 m0, s21
	s_add_u32 s6, s22, 0x80000
	global_load_lds_dwordx4 v136, s[22:23]
	s_mov_b32 m0, s34
	s_addc_u32 s7, s23, 0
	s_add_i32 s35, s21, 0x4000
	global_load_lds_dwordx4 v132, s[22:23]
	s_mov_b32 m0, s35
	s_add_i32 s38, s21, 0x6000
	global_load_lds_dwordx4 v136, s[6:7]
	s_mov_b32 m0, s38
	v_mov_b32_e32 v135, 0
	global_load_lds_dwordx4 v132, s[6:7]
	v_mov_b32_e32 v131, v135
	v_mov_b32_e32 v137, v135
	v_mov_b32_e32 v133, v135
	s_cmp_eq_u32 s12, 1
	s_mov_b32 s39, 0
	v_lshl_add_u64 v[8:9], s[24:25], 0, v[134:135]
	v_lshl_add_u64 v[6:7], s[24:25], 0, v[130:131]
	v_lshl_add_u64 v[2:3], s[22:23], 0, v[136:137]
	s_cselect_b64 s[6:7], -1, 0
	s_cmp_lg_u32 s12, 1
	v_lshl_add_u64 v[4:5], s[22:23], 0, v[132:133]
	s_cbranch_scc1 .LBB0_1697
	s_barrier
.LBB0_1697:
	s_lshl_b32 s8, s8, 5
	s_and_b32 s14, s8, 0x60
	s_mov_b64 s[8:9], 0x80
	s_add_i32 m0, s21, 0x18000
	v_lshl_add_u64 v[8:9], v[8:9], 0, s[8:9]
	s_lshl_b32 s13, s12, 13
	s_lshl_b32 s15, s14, 7
	s_waitcnt vmcnt(2)
	s_movk_i32 s98, 0x100
	v_cmp_gt_u32_e64 s[100:101], s98, v1
	s_nop 1
	s_and_saveexec_b64 s[100:101], s[100:101]
	s_cbranch_execz .Lrs_done_3
	v_mov_b32_e32 v252, 0x358637bd
	v_mov_b32_e32 v253, 0x800000
	v_fmac_f32_e32 v252, 0x3a000000, v250
	v_lshlrev_b32_e32 v251, 2, v1
	v_mul_f32_e32 v250, 0x4b800000, v252
	v_cmp_gt_f32_e64 s[98:99], v253, v252
	v_add_u32_e32 v251, 0x20000, v251
	s_nop 1
	v_cndmask_b32_e64 v250, v252, v250, s[98:99]
	v_rsq_f32_e32 v250, v250
	s_nop 0
	v_mul_f32_e32 v252, 0x45800000, v250
	v_cndmask_b32_e64 v250, v250, v252, s[98:99]
	ds_write_b32 v251, v250
.Lrs_done_3:
	s_or_b64 exec, exec, s[100:101]
	s_waitcnt lgkmcnt(0)
	s_barrier
	global_load_lds_dwordx4 v[8:9], off
	v_lshl_add_u64 v[6:7], v[6:7], 0, s[8:9]
	s_add_i32 m0, s21, 0x1a000
	s_add_i32 s40, s21, 0x8000
	s_add_i32 s41, s21, 0xa000
	global_load_lds_dwordx4 v[6:7], off
	v_lshl_add_u64 v[2:3], v[2:3], 0, s[8:9]
	s_mov_b32 m0, s40
	s_add_u32 s10, s24, 0x80080
	global_load_lds_dwordx4 v[2:3], off
	v_lshl_add_u64 v[2:3], v[4:5], 0, s[8:9]
	s_mov_b32 m0, s41
	s_addc_u32 s11, s25, 0
	global_load_lds_dwordx4 v[2:3], off
	s_add_i32 m0, s21, 0x1c000
	v_lshl_add_u64 v[2:3], s[10:11], 0, v[134:135]
	global_load_lds_dwordx4 v[2:3], off
	v_lshl_add_u64 v[2:3], s[10:11], 0, v[130:131]
	s_add_i32 m0, s21, 0x1e000
	s_sext_i32_i16 s46, s2
	global_load_lds_dwordx4 v[2:3], off
	v_and_b32_e32 v2, 15, v1
	v_lshlrev_b32_e32 v3, 1, v13
	v_lshl_or_b32 v146, s12, 6, v2
	v_lshl_or_b32 v4, v2, 6, v3
	v_lshlrev_b32_e32 v2, 2, v2
	v_and_b32_e32 v5, 32, v2
	v_bitop3_b32 v4, v4, s13, v5 bitop3:0xde
	v_lshlrev_b32_e32 v5, 6, v1
	s_movk_i32 s2, 0x3c0
	s_cmpk_lt_u32 s3, 0x100
	v_and_or_b32 v3, v5, s2, v3
	s_cselect_b64 s[10:11], -1, 0
	s_lshl_b32 s2, s12, 8
	v_lshlrev_b32_e32 v5, 2, v1
	s_add_i32 s2, s2, 0x20000
	v_and_b32_e32 v5, 32, v5
	v_or_b32_e32 v148, s2, v2
	v_lshlrev_b32_e32 v2, 9, v1
	v_bitop3_b32 v147, s15, v3, v5 bitop3:0xf6
	v_and_b32_e32 v2, 0x70000, v2
	v_lshlrev_b32_e32 v3, 12, v14
	v_or3_b32 v2, v11, v2, v3
	v_add_u32_e32 v138, v2, v12
	v_lshlrev_b32_e32 v2, 5, v10
	s_waitcnt vmcnt(6)
	v_and_b32_e32 v2, 0xf0000, v2
	v_or3_b32 v2, v11, v2, v3
	s_add_i32 s43, 0, 0x10000
	s_add_i32 s44, 0, 0x14000
	s_ashr_i32 s42, s86, 31
	v_or_b32_e32 v149, s14, v13
	v_mov_b32_e32 v139, v135
	v_add_u32_e32 v140, v2, v12
	v_mov_b32_e32 v141, v135
	v_mov_b64_e32 v[142:143], 0x580
	v_mov_b64_e32 v[144:145], 0x57f
	v_add_u32_e32 v150, s43, v147
	v_add_u32_e32 v151, s44, v147
	v_add_u32_e32 v152, 0, v4
	s_movk_i32 s45, 0x2c00
	s_barrier
	s_branch .LBB0_1700

; __device__ __forceinline__ float bflo(unsigned w) { return __uint_as_float(w << 16); }
; __device__ __forceinline__ float bfhi(unsigned w) { return __uint_as_float(w & 0xffff0000u); }
;     __device__ __forceinline__ void fused(f32x4 (&acc)[2][2][4][2], const Unit& u, int wr, int wc, int fr, int fq, PG8_LAS unsigned char* lds, int wid, int lane) const {
;     ...
; #pragma unroll
;         for (int ai = 0; ai < 2; ++ai)
; #pragma unroll
;             for (int m = 0; m < 4; ++m) {
;                 const int rl = ai * 128 + wr * 64 + m * 16 + fr; float s = 0.f;
; #pragma unroll
;                 for (int bj = 0; bj < 2; ++bj) {
;                     const size_t off = (size_t)(u.pm * 256 + rl) * D + col0 + bj * 128;
;                     const u32x4 w = *(const u32x4*)(xb + off);
;                     const f32x4 b0 = (f32x4){bflo(w.x), bfhi(w.x), bflo(w.y), bfhi(w.y)}, b1 = (f32x4){bflo(w.z), bfhi(w.z), bflo(w.w), bfhi(w.w)};
;                     const f32x4 h0 = b0 + acc[ai][bj][m][0] * scale, h1 = b1 + acc[ai][bj][m][1] * scale;
;                     acc[ai][bj][m][0] = h0; acc[ai][bj][m][1] = h1;
;                     s += (h0[0] * h0[0] + h0[1] * h0[1]) + (h0[2] * h0[2] + h0[3] * h0[3]) + (h1[0] * h1[0] + h1[1] * h1[1]) + (h1[2] * h1[2] + h1[3] * h1[3]);
;                 }
;                 s += __shfl_xor(s, 16); s += __shfl_xor(s, 32);
;                 if (fq == 0) P[rl * 4 + wc] = s;
;             }
.LBB0_1911:
	s_lshl_b32 s4, s27, 8
	s_lshl_b32 s0, s29, 5
	s_lshl_b32 s1, s10, 8
	v_add_u32_e32 v130, s4, v164
	s_or_b32 s0, s1, s0
	v_ashrrev_i32_e32 v131, 31, v130
	v_and_or_b32 v132, v150, 24, s0
	v_lshlrev_b64 v[134:135], 12, v[130:131]
	v_ashrrev_i32_e32 v133, 31, v132
	v_lshl_add_u64 v[134:135], s[36:37], 0, v[134:135]
	v_lshl_add_u64 v[138:139], v[132:133], 1, v[134:135]
	s_barrier
	v_mov_b64_e32 v[188:189], v[138:139]
	global_load_dwordx4 v[192:195], v[188:189], off
	global_load_dwordx4 v[196:199], v[188:189], off offset:256
	s_mov_b64 s[100:101], 0x10000
	v_lshl_add_u64 v[228:229], v[188:189], 0, s[100:101]
	global_load_dwordx4 v[200:203], v[228:229], off
	global_load_dwordx4 v[204:207], v[228:229], off offset:256
	s_mov_b64 s[100:101], 0x20000
	v_lshl_add_u64 v[228:229], v[188:189], 0, s[100:101]
	global_load_dwordx4 v[208:211], v[228:229], off
	global_load_dwordx4 v[212:215], v[228:229], off offset:256
	s_mov_b64 s[100:101], 0x30000
	v_lshl_add_u64 v[228:229], v[188:189], 0, s[100:101]
	global_load_dwordx4 v[216:219], v[228:229], off
	global_load_dwordx4 v[220:223], v[228:229], off offset:256
	s_nop 0
	v_mbcnt_lo_u32_b32 v142, -1, 0
	v_mbcnt_hi_u32_b32 v150, -1, v142
	v_and_b32_e32 v143, 64, v150
	v_xor_b32_e32 v142, 16, v150
	v_add_u32_e32 v151, 64, v143
	v_cmp_lt_i32_e32 vcc, v142, v151
	s_lshl_b32 s0, s29, 2
	s_add_i32 s2, s0, 0
	v_cndmask_b32_e32 v142, v150, v142, vcc
	v_lshlrev_b32_e32 v165, 2, v142
	s_waitcnt vmcnt(6)
	v_lshlrev_b32_e32 v142, 16, v192
	v_and_b32_e32 v143, 0xffff0000, v192
	v_lshlrev_b32_e32 v134, 16, v193
	v_and_b32_e32 v135, 0xffff0000, v193
	v_lshlrev_b32_e32 v146, 16, v196
	v_and_b32_e32 v147, 0xffff0000, v196
	v_lshlrev_b32_e32 v138, 16, v197
	v_and_b32_e32 v139, 0xffff0000, v197
	v_lshlrev_b32_e32 v144, 16, v194
	v_and_b32_e32 v145, 0xffff0000, v194
	v_lshlrev_b32_e32 v148, 16, v198
	v_and_b32_e32 v149, 0xffff0000, v198
	v_pk_fma_f32 v[128:129], v[128:129], 0.5, v[134:135] op_sel_hi:[1,0,1]
	v_pk_fma_f32 v[126:127], v[126:127], 0.5, v[142:143] op_sel_hi:[1,0,1]
	v_pk_fma_f32 v[120:121], v[120:121], 0.5, v[138:139] op_sel_hi:[1,0,1]
	v_pk_fma_f32 v[118:119], v[118:119], 0.5, v[146:147] op_sel_hi:[1,0,1]
	v_lshlrev_b32_e32 v136, 16, v195
	v_and_b32_e32 v137, 0xffff0000, v195
	v_lshlrev_b32_e32 v140, 16, v199
	v_and_b32_e32 v141, 0xffff0000, v199
	s_mov_b64 s[100:101], 0x80000
	v_lshl_add_u64 v[228:229], v[188:189], 0, s[100:101]
	global_load_dwordx4 v[192:195], v[228:229], off
	global_load_dwordx4 v[196:199], v[228:229], off offset:256
	v_pk_fma_f32 v[122:123], v[122:123], 0.5, v[144:145] op_sel_hi:[1,0,1]
	v_pk_fma_f32 v[114:115], v[114:115], 0.5, v[148:149] op_sel_hi:[1,0,1]
	v_mul_f32_e32 v134, v127, v127
	v_mul_f32_e32 v135, v129, v129
	v_mul_f32_e32 v138, v119, v119
	v_mul_f32_e32 v139, v121, v121
	v_pk_fma_f32 v[124:125], v[124:125], 0.5, v[136:137] op_sel_hi:[1,0,1]
	v_pk_fma_f32 v[116:117], v[116:117], 0.5, v[140:141] op_sel_hi:[1,0,1]
	v_mul_f32_e32 v136, v123, v123
	v_mul_f32_e32 v140, v115, v115
	v_fmac_f32_e32 v134, v126, v126
	v_fmac_f32_e32 v135, v128, v128
	v_fmac_f32_e32 v138, v118, v118
	v_fmac_f32_e32 v139, v120, v120
	v_mul_f32_e32 v137, v125, v125
	v_mul_f32_e32 v141, v117, v117
	v_fmac_f32_e32 v136, v122, v122
	v_fmac_f32_e32 v140, v114, v114
	v_add_f32_e32 v134, v134, v135
	v_add_f32_e32 v135, v138, v139
	v_fmac_f32_e32 v137, v124, v124
	v_fmac_f32_e32 v141, v116, v116
	v_add_f32_e32 v134, v136, v134
	v_add_f32_e32 v135, v140, v135
	v_add_f32_e32 v134, v137, v134
	v_add_f32_e32 v135, v141, v135
	v_add_f32_e32 v134, v134, v135
	ds_bpermute_b32 v135, v165, v134
	v_xor_b32_e32 v136, 32, v150
	v_cmp_lt_i32_e32 vcc, v136, v151
	s_waitcnt lgkmcnt(0)
	v_add_f32_e32 v134, v134, v135
	v_cndmask_b32_e32 v136, v150, v136, vcc
	v_lshlrev_b32_e32 v166, 2, v136
	ds_bpermute_b32 v135, v166, v134
	v_cmp_gt_u32_e32 vcc, 16, v190
	s_and_saveexec_b64 s[0:1], vcc
	s_cbranch_execz .LBB0_1913
	v_lshl_add_u32 v136, v164, 4, s2
	s_waitcnt lgkmcnt(0)
	v_add_f32_e32 v134, v134, v135
	ds_write_b32 v136, v134
.LBB0_1913:
	s_or_b64 exec, exec, s[0:1]
	v_or_b32_e32 v136, 16, v164
	v_add_u32_e32 v134, s4, v136
	s_waitcnt lgkmcnt(0)
	v_ashrrev_i32_e32 v135, 31, v134
	v_lshlrev_b64 v[138:139], 12, v[134:135]
	v_lshl_add_u64 v[138:139], s[36:37], 0, v[138:139]
	v_lshl_add_u64 v[142:143], v[132:133], 1, v[138:139]
	s_nop 0
	s_waitcnt vmcnt(7)
	v_lshlrev_b32_e32 v146, 16, v200
	v_and_b32_e32 v147, 0xffff0000, v200
	v_lshlrev_b32_e32 v138, 16, v201
	v_and_b32_e32 v139, 0xffff0000, v201
	s_waitcnt vmcnt(6)
	v_lshlrev_b32_e32 v150, 16, v204
	v_and_b32_e32 v151, 0xffff0000, v204
	v_lshlrev_b32_e32 v142, 16, v205
	v_and_b32_e32 v143, 0xffff0000, v205
	v_lshlrev_b32_e32 v148, 16, v202
	v_and_b32_e32 v149, 0xffff0000, v202
	v_lshlrev_b32_e32 v140, 16, v203
	v_and_b32_e32 v141, 0xffff0000, v203
	v_lshlrev_b32_e32 v152, 16, v206
	v_and_b32_e32 v153, 0xffff0000, v206
	v_pk_fma_f32 v[112:113], v[112:113], 0.5, v[138:139] op_sel_hi:[1,0,1]
	v_pk_fma_f32 v[110:111], v[110:111], 0.5, v[146:147] op_sel_hi:[1,0,1]
	v_pk_fma_f32 v[104:105], v[104:105], 0.5, v[142:143] op_sel_hi:[1,0,1]
	v_pk_fma_f32 v[102:103], v[102:103], 0.5, v[150:151] op_sel_hi:[1,0,1]
	v_lshlrev_b32_e32 v144, 16, v207
	v_and_b32_e32 v145, 0xffff0000, v207
	s_mov_b64 s[100:101], 0x90000
	v_lshl_add_u64 v[228:229], v[188:189], 0, s[100:101]
	global_load_dwordx4 v[200:203], v[228:229], off
	global_load_dwordx4 v[204:207], v[228:229], off offset:256
	v_pk_fma_f32 v[108:109], v[108:109], 0.5, v[140:141] op_sel_hi:[1,0,1]
	v_pk_fma_f32 v[106:107], v[106:107], 0.5, v[148:149] op_sel_hi:[1,0,1]
	v_pk_fma_f32 v[98:99], v[98:99], 0.5, v[152:153] op_sel_hi:[1,0,1]
	v_mul_f32_e32 v137, v111, v111
	v_mul_f32_e32 v138, v113, v113
	v_mul_f32_e32 v141, v103, v103
	v_mul_f32_e32 v142, v105, v105
	v_pk_fma_f32 v[100:101], v[100:101], 0.5, v[144:145] op_sel_hi:[1,0,1]
	v_mul_f32_e32 v139, v107, v107
	v_mul_f32_e32 v143, v99, v99
	v_fmac_f32_e32 v137, v110, v110
	v_fmac_f32_e32 v138, v112, v112
	v_fmac_f32_e32 v141, v102, v102
	v_fmac_f32_e32 v142, v104, v104
	v_mul_f32_e32 v140, v109, v109
	v_mul_f32_e32 v144, v101, v101
	v_fmac_f32_e32 v139, v106, v106
	v_fmac_f32_e32 v143, v98, v98
	v_add_f32_e32 v137, v137, v138
	v_add_f32_e32 v138, v141, v142
	v_fmac_f32_e32 v140, v108, v108
	v_fmac_f32_e32 v144, v100, v100
	v_add_f32_e32 v137, v139, v137
	v_add_f32_e32 v138, v143, v138
	v_add_f32_e32 v137, v140, v137
	v_add_f32_e32 v138, v144, v138
	v_add_f32_e32 v137, v137, v138
	ds_bpermute_b32 v138, v165, v137
	s_waitcnt lgkmcnt(0)
	v_add_f32_e32 v137, v137, v138
	ds_bpermute_b32 v138, v166, v137
	s_and_saveexec_b64 s[0:1], vcc
	s_cbranch_execz .LBB0_1915
	v_lshl_add_u32 v136, v136, 4, s2
	s_waitcnt lgkmcnt(0)
	v_add_f32_e32 v137, v137, v138
	ds_write_b32 v136, v137
; __device__ __forceinline__ float bflo(unsigned w) { return __uint_as_float(w << 16); }
; __device__ __forceinline__ float bfhi(unsigned w) { return __uint_as_float(w & 0xffff0000u); }
;     __device__ __forceinline__ void fused(f32x4 (&acc)[2][2][4][2], const Unit& u, int wr, int wc, int fr, int fq, PG8_LAS unsigned char* lds, int wid, int lane) const {
;     ...
; #pragma unroll
;         for (int ai = 0; ai < 2; ++ai)
; #pragma unroll
;             for (int m = 0; m < 4; ++m) {
;                 const int rl = ai * 128 + wr * 64 + m * 16 + fr; float s = 0.f;
; #pragma unroll
;                 for (int bj = 0; bj < 2; ++bj) {
;                     const size_t off = (size_t)(u.pm * 256 + rl) * D + col0 + bj * 128;
;                     const u32x4 w = *(const u32x4*)(xb + off);
;                     const f32x4 b0 = (f32x4){bflo(w.x), bfhi(w.x), bflo(w.y), bfhi(w.y)}, b1 = (f32x4){bflo(w.z), bfhi(w.z), bflo(w.w), bfhi(w.w)};
;                     const f32x4 h0 = b0 + acc[ai][bj][m][0] * scale, h1 = b1 + acc[ai][bj][m][1] * scale;
;                     acc[ai][bj][m][0] = h0; acc[ai][bj][m][1] = h1;
;                     s += (h0[0] * h0[0] + h0[1] * h0[1]) + (h0[2] * h0[2] + h0[3] * h0[3]) + (h1[0] * h1[0] + h1[1] * h1[1]) + (h1[2] * h1[2] + h1[3] * h1[3]);
;                 }
;                 s += __shfl_xor(s, 16); s += __shfl_xor(s, 32);
;                 if (fq == 0) P[rl * 4 + wc] = s;
;             }
.LBB0_1915:
	s_or_b64 exec, exec, s[0:1]
	v_or_b32_e32 v140, 32, v164
	v_add_u32_e32 v136, s4, v140
	v_ashrrev_i32_e32 v137, 31, v136
	s_waitcnt lgkmcnt(0)
	v_lshlrev_b64 v[138:139], 12, v[136:137]
	v_lshl_add_u64 v[138:139], s[36:37], 0, v[138:139]
	v_lshl_add_u64 v[138:139], v[132:133], 1, v[138:139]
	s_waitcnt vmcnt(7)
	v_lshlrev_b32_e32 v138, 16, v208
	v_and_b32_e32 v139, 0xffff0000, v208
	v_lshlrev_b32_e32 v142, 16, v209
	v_and_b32_e32 v143, 0xffff0000, v209
	v_lshlrev_b32_e32 v150, 16, v210
	v_and_b32_e32 v151, 0xffff0000, v210
	s_waitcnt vmcnt(6)
	v_lshlrev_b32_e32 v152, 16, v212
	v_and_b32_e32 v153, 0xffff0000, v212
	v_lshlrev_b32_e32 v146, 16, v213
	v_and_b32_e32 v147, 0xffff0000, v213
	v_lshlrev_b32_e32 v144, 16, v211
	v_and_b32_e32 v145, 0xffff0000, v211
	v_lshlrev_b32_e32 v154, 16, v214
	v_and_b32_e32 v155, 0xffff0000, v214
	v_pk_fma_f32 v[96:97], v[96:97], 0.5, v[142:143] op_sel_hi:[1,0,1]
	v_pk_fma_f32 v[138:139], v[94:95], 0.5, v[138:139] op_sel_hi:[1,0,1]
	v_pk_fma_f32 v[94:95], v[90:91], 0.5, v[150:151] op_sel_hi:[1,0,1]
	v_pk_fma_f32 v[88:89], v[88:89], 0.5, v[146:147] op_sel_hi:[1,0,1]
	v_pk_fma_f32 v[90:91], v[86:87], 0.5, v[152:153] op_sel_hi:[1,0,1]
	v_lshlrev_b32_e32 v148, 16, v215
	v_and_b32_e32 v149, 0xffff0000, v215
	s_mov_b64 s[100:101], 0xa0000
	v_lshl_add_u64 v[228:229], v[188:189], 0, s[100:101]
	global_load_dwordx4 v[208:211], v[228:229], off
	global_load_dwordx4 v[212:215], v[228:229], off offset:256
	v_pk_fma_f32 v[92:93], v[92:93], 0.5, v[144:145] op_sel_hi:[1,0,1]
	v_pk_fma_f32 v[86:87], v[82:83], 0.5, v[154:155] op_sel_hi:[1,0,1]
	v_mul_f32_e32 v82, v139, v139
	v_mul_f32_e32 v83, v97, v97
	v_mul_f32_e32 v143, v91, v91
	v_mul_f32_e32 v144, v89, v89
	v_pk_fma_f32 v[84:85], v[84:85], 0.5, v[148:149] op_sel_hi:[1,0,1]
	v_mul_f32_e32 v141, v95, v95
	v_mul_f32_e32 v145, v87, v87
	v_fmac_f32_e32 v82, v138, v138
	v_fmac_f32_e32 v83, v96, v96
	v_fmac_f32_e32 v143, v90, v90
	v_fmac_f32_e32 v144, v88, v88
	v_mul_f32_e32 v142, v93, v93
	v_mul_f32_e32 v146, v85, v85
	v_fmac_f32_e32 v141, v94, v94
	v_fmac_f32_e32 v145, v86, v86
	v_add_f32_e32 v82, v82, v83
	v_add_f32_e32 v83, v143, v144
	v_fmac_f32_e32 v142, v92, v92
	v_fmac_f32_e32 v146, v84, v84
	v_add_f32_e32 v82, v141, v82
	v_add_f32_e32 v83, v145, v83
	v_add_f32_e32 v82, v142, v82
	v_add_f32_e32 v83, v146, v83
	v_add_f32_e32 v82, v82, v83
	ds_bpermute_b32 v83, v165, v82
	s_waitcnt lgkmcnt(0)
	v_add_f32_e32 v82, v82, v83
	ds_bpermute_b32 v83, v166, v82
	s_and_saveexec_b64 s[0:1], vcc
	s_cbranch_execz .LBB0_1917
	v_lshl_add_u32 v140, v140, 4, s2
	s_waitcnt lgkmcnt(0)
	v_add_f32_e32 v82, v82, v83
	ds_write_b32 v140, v82
.LBB0_1917:
	s_or_b64 exec, exec, s[0:1]
	v_or_b32_e32 v140, 48, v164
	v_add_u32_e32 v82, s4, v140
	s_waitcnt lgkmcnt(0)
	v_ashrrev_i32_e32 v83, 31, v82
	v_lshlrev_b64 v[142:143], 12, v[82:83]
	v_lshl_add_u64 v[142:143], s[36:37], 0, v[142:143]
	v_lshl_add_u64 v[146:147], v[132:133], 1, v[142:143]
	s_nop 0
	s_waitcnt vmcnt(7)
	v_lshlrev_b32_e32 v150, 16, v216
	v_and_b32_e32 v151, 0xffff0000, v216
	v_lshlrev_b32_e32 v142, 16, v217
	v_and_b32_e32 v143, 0xffff0000, v217
	s_waitcnt vmcnt(6)
	v_lshlrev_b32_e32 v154, 16, v220
	v_and_b32_e32 v155, 0xffff0000, v220
	v_lshlrev_b32_e32 v146, 16, v221
	v_and_b32_e32 v147, 0xffff0000, v221
	v_lshlrev_b32_e32 v152, 16, v218
	v_and_b32_e32 v153, 0xffff0000, v218
	v_lshlrev_b32_e32 v144, 16, v219
	v_and_b32_e32 v145, 0xffff0000, v219
	v_lshlrev_b32_e32 v156, 16, v222
	v_and_b32_e32 v157, 0xffff0000, v222
	v_pk_fma_f32 v[80:81], v[80:81], 0.5, v[142:143] op_sel_hi:[1,0,1]
	v_pk_fma_f32 v[78:79], v[78:79], 0.5, v[150:151] op_sel_hi:[1,0,1]
	v_pk_fma_f32 v[72:73], v[72:73], 0.5, v[146:147] op_sel_hi:[1,0,1]
	v_pk_fma_f32 v[70:71], v[70:71], 0.5, v[154:155] op_sel_hi:[1,0,1]
	v_lshlrev_b32_e32 v148, 16, v223
	v_and_b32_e32 v149, 0xffff0000, v223
	s_mov_b64 s[100:101], 0xb0000
	v_lshl_add_u64 v[228:229], v[188:189], 0, s[100:101]
	global_load_dwordx4 v[216:219], v[228:229], off
	global_load_dwordx4 v[220:223], v[228:229], off offset:256
	v_pk_fma_f32 v[76:77], v[76:77], 0.5, v[144:145] op_sel_hi:[1,0,1]
	v_pk_fma_f32 v[74:75], v[74:75], 0.5, v[152:153] op_sel_hi:[1,0,1]
	v_pk_fma_f32 v[66:67], v[66:67], 0.5, v[156:157] op_sel_hi:[1,0,1]
	v_mul_f32_e32 v141, v79, v79
	v_mul_f32_e32 v142, v81, v81
	v_mul_f32_e32 v145, v71, v71
	v_mul_f32_e32 v146, v73, v73
	v_pk_fma_f32 v[68:69], v[68:69], 0.5, v[148:149] op_sel_hi:[1,0,1]
	v_mul_f32_e32 v143, v75, v75
	v_mul_f32_e32 v147, v67, v67
	v_fmac_f32_e32 v141, v78, v78
	v_fmac_f32_e32 v142, v80, v80
	v_fmac_f32_e32 v145, v70, v70
	v_fmac_f32_e32 v146, v72, v72
	v_mul_f32_e32 v144, v77, v77
	v_mul_f32_e32 v148, v69, v69
	v_fmac_f32_e32 v143, v74, v74
	v_fmac_f32_e32 v147, v66, v66
	v_add_f32_e32 v141, v141, v142
	v_add_f32_e32 v142, v145, v146
	v_fmac_f32_e32 v144, v76, v76
	v_fmac_f32_e32 v148, v68, v68
	v_add_f32_e32 v141, v143, v141
	v_add_f32_e32 v142, v147, v142
	v_add_f32_e32 v141, v144, v141
	v_add_f32_e32 v142, v148, v142
	v_add_f32_e32 v141, v141, v142
	ds_bpermute_b32 v142, v165, v141
	s_waitcnt lgkmcnt(0)
	v_add_f32_e32 v141, v141, v142
	ds_bpermute_b32 v142, v166, v141
	s_and_saveexec_b64 s[0:1], vcc
	s_cbranch_execz .LBB0_1919
	v_lshl_add_u32 v140, v140, 4, s2
	s_waitcnt lgkmcnt(0)
	v_add_f32_e32 v141, v141, v142
	ds_write_b32 v140, v141
; __device__ __forceinline__ float bflo(unsigned w) { return __uint_as_float(w << 16); }
; __device__ __forceinline__ float bfhi(unsigned w) { return __uint_as_float(w & 0xffff0000u); }
;     __device__ __forceinline__ void fused(f32x4 (&acc)[2][2][4][2], const Unit& u, int wr, int wc, int fr, int fq, PG8_LAS unsigned char* lds, int wid, int lane) const {
;     ...
;                 const int rl = ai * 128 + wr * 64 + m * 16 + fr; float s = 0.f;
; #pragma unroll
;                 for (int bj = 0; bj < 2; ++bj) {
;                     const size_t off = (size_t)(u.pm * 256 + rl) * D + col0 + bj * 128;
;                     const u32x4 w = *(const u32x4*)(xb + off);
;                     const f32x4 b0 = (f32x4){bflo(w.x), bfhi(w.x), bflo(w.y), bfhi(w.y)}, b1 = (f32x4){bflo(w.z), bfhi(w.z), bflo(w.w), bfhi(w.w)};
;                     const f32x4 h0 = b0 + acc[ai][bj][m][0] * scale, h1 = b1 + acc[ai][bj][m][1] * scale;
;                     acc[ai][bj][m][0] = h0; acc[ai][bj][m][1] = h1;
;                     s += (h0[0] * h0[0] + h0[1] * h0[1]) + (h0[2] * h0[2] + h0[3] * h0[3]) + (h1[0] * h1[0] + h1[1] * h1[1]) + (h1[2] * h1[2] + h1[3] * h1[3]);
;                 }
;                 s += __shfl_xor(s, 16); s += __shfl_xor(s, 32);
;                 if (fq == 0) P[rl * 4 + wc] = s;
.LBB0_1919:
	s_or_b64 exec, exec, s[0:1]
	s_waitcnt lgkmcnt(0)
	v_add_u32_e32 v142, 0x80, v164
	v_add_u32_e32 v140, s4, v142
	v_ashrrev_i32_e32 v141, 31, v140
	v_lshlrev_b64 v[144:145], 12, v[140:141]
	v_lshl_add_u64 v[144:145], s[36:37], 0, v[144:145]
	v_lshl_add_u64 v[148:149], v[132:133], 1, v[144:145]
	s_nop 0
	s_waitcnt vmcnt(7)
	v_lshlrev_b32_e32 v152, 16, v192
	v_and_b32_e32 v153, 0xffff0000, v192
	v_lshlrev_b32_e32 v144, 16, v193
	v_and_b32_e32 v145, 0xffff0000, v193
	s_waitcnt vmcnt(6)
	v_lshlrev_b32_e32 v156, 16, v196
	v_and_b32_e32 v157, 0xffff0000, v196
	v_lshlrev_b32_e32 v148, 16, v197
	v_and_b32_e32 v149, 0xffff0000, v197
	v_lshlrev_b32_e32 v154, 16, v194
	v_and_b32_e32 v155, 0xffff0000, v194
	v_lshlrev_b32_e32 v146, 16, v195
	v_and_b32_e32 v147, 0xffff0000, v195
	v_lshlrev_b32_e32 v158, 16, v198
	v_and_b32_e32 v159, 0xffff0000, v198
	v_pk_fma_f32 v[64:65], v[64:65], 0.5, v[144:145] op_sel_hi:[1,0,1]
	v_pk_fma_f32 v[62:63], v[62:63], 0.5, v[152:153] op_sel_hi:[1,0,1]
	v_pk_fma_f32 v[56:57], v[56:57], 0.5, v[148:149] op_sel_hi:[1,0,1]
	v_pk_fma_f32 v[54:55], v[54:55], 0.5, v[156:157] op_sel_hi:[1,0,1]
	v_lshlrev_b32_e32 v150, 16, v199
	v_and_b32_e32 v151, 0xffff0000, v199
	v_pk_fma_f32 v[60:61], v[60:61], 0.5, v[146:147] op_sel_hi:[1,0,1]
	v_pk_fma_f32 v[58:59], v[58:59], 0.5, v[154:155] op_sel_hi:[1,0,1]
	v_pk_fma_f32 v[50:51], v[50:51], 0.5, v[158:159] op_sel_hi:[1,0,1]
	v_mul_f32_e32 v143, v63, v63
	v_mul_f32_e32 v144, v65, v65
	v_mul_f32_e32 v147, v55, v55
	v_mul_f32_e32 v148, v57, v57
	v_pk_fma_f32 v[52:53], v[52:53], 0.5, v[150:151] op_sel_hi:[1,0,1]
	v_mul_f32_e32 v145, v59, v59
	v_mul_f32_e32 v149, v51, v51
	v_fmac_f32_e32 v143, v62, v62
	v_fmac_f32_e32 v144, v64, v64
	v_fmac_f32_e32 v147, v54, v54
	v_fmac_f32_e32 v148, v56, v56
	v_mul_f32_e32 v146, v61, v61
	v_mul_f32_e32 v150, v53, v53
	v_fmac_f32_e32 v145, v58, v58
	v_fmac_f32_e32 v149, v50, v50
	v_add_f32_e32 v143, v143, v144
	v_add_f32_e32 v144, v147, v148
	v_fmac_f32_e32 v146, v60, v60
	v_fmac_f32_e32 v150, v52, v52
	v_add_f32_e32 v143, v145, v143
	v_add_f32_e32 v144, v149, v144
	v_add_f32_e32 v143, v146, v143
	v_add_f32_e32 v144, v150, v144
	v_add_f32_e32 v143, v143, v144
	ds_bpermute_b32 v144, v165, v143
	s_waitcnt lgkmcnt(0)
	v_add_f32_e32 v143, v143, v144
	ds_bpermute_b32 v144, v166, v143
	s_and_saveexec_b64 s[0:1], vcc
	s_cbranch_execz .LBB0_1921
	v_lshl_add_u32 v142, v142, 4, s2
	s_waitcnt lgkmcnt(0)
	v_add_f32_e32 v143, v143, v144
	ds_write_b32 v142, v143
.LBB0_1921:
	s_or_b64 exec, exec, s[0:1]
	s_waitcnt lgkmcnt(0)
	v_add_u32_e32 v144, 0x90, v164
	v_add_u32_e32 v142, s4, v144
	v_ashrrev_i32_e32 v143, 31, v142
	v_lshlrev_b64 v[146:147], 12, v[142:143]
	v_lshl_add_u64 v[146:147], s[36:37], 0, v[146:147]
	v_lshl_add_u64 v[150:151], v[132:133], 1, v[146:147]
	s_nop 0
	s_waitcnt vmcnt(5)
	v_lshlrev_b32_e32 v154, 16, v200
	v_and_b32_e32 v155, 0xffff0000, v200
	v_lshlrev_b32_e32 v146, 16, v201
	v_and_b32_e32 v147, 0xffff0000, v201
	s_waitcnt vmcnt(4)
	v_lshlrev_b32_e32 v158, 16, v204
	v_and_b32_e32 v159, 0xffff0000, v204
	v_lshlrev_b32_e32 v150, 16, v205
	v_and_b32_e32 v151, 0xffff0000, v205
	v_lshlrev_b32_e32 v156, 16, v202
	v_and_b32_e32 v157, 0xffff0000, v202
	v_lshlrev_b32_e32 v148, 16, v203
	v_and_b32_e32 v149, 0xffff0000, v203
	v_lshlrev_b32_e32 v160, 16, v206
	v_and_b32_e32 v161, 0xffff0000, v206
	v_pk_fma_f32 v[48:49], v[48:49], 0.5, v[146:147] op_sel_hi:[1,0,1]
	v_pk_fma_f32 v[46:47], v[46:47], 0.5, v[154:155] op_sel_hi:[1,0,1]
	v_pk_fma_f32 v[40:41], v[40:41], 0.5, v[150:151] op_sel_hi:[1,0,1]
	v_pk_fma_f32 v[38:39], v[38:39], 0.5, v[158:159] op_sel_hi:[1,0,1]
	v_lshlrev_b32_e32 v152, 16, v207
	v_and_b32_e32 v153, 0xffff0000, v207
	v_pk_fma_f32 v[44:45], v[44:45], 0.5, v[148:149] op_sel_hi:[1,0,1]
	v_pk_fma_f32 v[42:43], v[42:43], 0.5, v[156:157] op_sel_hi:[1,0,1]
	v_pk_fma_f32 v[34:35], v[34:35], 0.5, v[160:161] op_sel_hi:[1,0,1]
	v_mul_f32_e32 v145, v47, v47
	v_mul_f32_e32 v146, v49, v49
	v_mul_f32_e32 v149, v39, v39
	v_mul_f32_e32 v150, v41, v41
	v_pk_fma_f32 v[36:37], v[36:37], 0.5, v[152:153] op_sel_hi:[1,0,1]
	v_mul_f32_e32 v147, v43, v43
	v_mul_f32_e32 v151, v35, v35
	v_fmac_f32_e32 v145, v46, v46
	v_fmac_f32_e32 v146, v48, v48
	v_fmac_f32_e32 v149, v38, v38
	v_fmac_f32_e32 v150, v40, v40
	v_mul_f32_e32 v148, v45, v45
	v_mul_f32_e32 v152, v37, v37
	v_fmac_f32_e32 v147, v42, v42
	v_fmac_f32_e32 v151, v34, v34
	v_add_f32_e32 v145, v145, v146
	v_add_f32_e32 v146, v149, v150
	v_fmac_f32_e32 v148, v44, v44
	v_fmac_f32_e32 v152, v36, v36
	v_add_f32_e32 v145, v147, v145
	v_add_f32_e32 v146, v151, v146
	v_add_f32_e32 v145, v148, v145
	v_add_f32_e32 v146, v152, v146
	v_add_f32_e32 v145, v145, v146
	ds_bpermute_b32 v146, v165, v145
	s_waitcnt lgkmcnt(0)
	v_add_f32_e32 v145, v145, v146
	ds_bpermute_b32 v146, v166, v145
	s_and_saveexec_b64 s[0:1], vcc
	s_cbranch_execz .LBB0_1923
	v_lshl_add_u32 v144, v144, 4, s2
	s_waitcnt lgkmcnt(0)
	v_add_f32_e32 v145, v145, v146
	ds_write_b32 v144, v145
; __device__ __forceinline__ float bflo(unsigned w) { return __uint_as_float(w << 16); }
; __device__ __forceinline__ float bfhi(unsigned w) { return __uint_as_float(w & 0xffff0000u); }
;     __device__ __forceinline__ void fused(f32x4 (&acc)[2][2][4][2], const Unit& u, int wr, int wc, int fr, int fq, PG8_LAS unsigned char* lds, int wid, int lane) const {
;     ...
;                 const int rl = ai * 128 + wr * 64 + m * 16 + fr; float s = 0.f;
; #pragma unroll
;                 for (int bj = 0; bj < 2; ++bj) {
;                     const size_t off = (size_t)(u.pm * 256 + rl) * D + col0 + bj * 128;
;                     const u32x4 w = *(const u32x4*)(xb + off);
;                     const f32x4 b0 = (f32x4){bflo(w.x), bfhi(w.x), bflo(w.y), bfhi(w.y)}, b1 = (f32x4){bflo(w.z), bfhi(w.z), bflo(w.w), bfhi(w.w)};
;                     const f32x4 h0 = b0 + acc[ai][bj][m][0] * scale, h1 = b1 + acc[ai][bj][m][1] * scale;
;                     acc[ai][bj][m][0] = h0; acc[ai][bj][m][1] = h1;
;                     s += (h0[0] * h0[0] + h0[1] * h0[1]) + (h0[2] * h0[2] + h0[3] * h0[3]) + (h1[0] * h1[0] + h1[1] * h1[1]) + (h1[2] * h1[2] + h1[3] * h1[3]);
;                 }
;                 s += __shfl_xor(s, 16); s += __shfl_xor(s, 32);
;                 if (fq == 0) P[rl * 4 + wc] = s;
.LBB0_1923:
	s_or_b64 exec, exec, s[0:1]
	s_waitcnt lgkmcnt(0)
	v_add_u32_e32 v146, 0xa0, v164
	v_add_u32_e32 v144, s4, v146
	v_ashrrev_i32_e32 v145, 31, v144
	v_lshlrev_b64 v[148:149], 12, v[144:145]
	v_lshl_add_u64 v[148:149], s[36:37], 0, v[148:149]
	v_lshl_add_u64 v[152:153], v[132:133], 1, v[148:149]
	s_nop 0
	s_waitcnt vmcnt(3)
	v_lshlrev_b32_e32 v156, 16, v208
	v_and_b32_e32 v157, 0xffff0000, v208
	v_lshlrev_b32_e32 v148, 16, v209
	v_and_b32_e32 v149, 0xffff0000, v209
	s_waitcnt vmcnt(2)
	v_lshlrev_b32_e32 v160, 16, v212
	v_and_b32_e32 v161, 0xffff0000, v212
	v_lshlrev_b32_e32 v152, 16, v213
	v_and_b32_e32 v153, 0xffff0000, v213
	v_lshlrev_b32_e32 v158, 16, v210
	v_and_b32_e32 v159, 0xffff0000, v210
	v_lshlrev_b32_e32 v150, 16, v211
	v_and_b32_e32 v151, 0xffff0000, v211
	v_lshlrev_b32_e32 v162, 16, v214
	v_and_b32_e32 v163, 0xffff0000, v214
	v_pk_fma_f32 v[32:33], v[32:33], 0.5, v[148:149] op_sel_hi:[1,0,1]
	v_pk_fma_f32 v[30:31], v[30:31], 0.5, v[156:157] op_sel_hi:[1,0,1]
	v_pk_fma_f32 v[24:25], v[24:25], 0.5, v[152:153] op_sel_hi:[1,0,1]
	v_pk_fma_f32 v[22:23], v[22:23], 0.5, v[160:161] op_sel_hi:[1,0,1]
	v_lshlrev_b32_e32 v154, 16, v215
	v_and_b32_e32 v155, 0xffff0000, v215
	v_pk_fma_f32 v[28:29], v[28:29], 0.5, v[150:151] op_sel_hi:[1,0,1]
	v_pk_fma_f32 v[26:27], v[26:27], 0.5, v[158:159] op_sel_hi:[1,0,1]
	v_pk_fma_f32 v[18:19], v[18:19], 0.5, v[162:163] op_sel_hi:[1,0,1]
	v_mul_f32_e32 v147, v31, v31
	v_mul_f32_e32 v148, v33, v33
	v_mul_f32_e32 v151, v23, v23
	v_mul_f32_e32 v152, v25, v25
	v_pk_fma_f32 v[20:21], v[20:21], 0.5, v[154:155] op_sel_hi:[1,0,1]
	v_mul_f32_e32 v149, v27, v27
	v_mul_f32_e32 v153, v19, v19
	v_fmac_f32_e32 v147, v30, v30
	v_fmac_f32_e32 v148, v32, v32
	v_fmac_f32_e32 v151, v22, v22
	v_fmac_f32_e32 v152, v24, v24
	v_mul_f32_e32 v150, v29, v29
	v_mul_f32_e32 v154, v21, v21
	v_fmac_f32_e32 v149, v26, v26
	v_fmac_f32_e32 v153, v18, v18
	v_add_f32_e32 v147, v147, v148
	v_add_f32_e32 v148, v151, v152
	v_fmac_f32_e32 v150, v28, v28
	v_fmac_f32_e32 v154, v20, v20
	v_add_f32_e32 v147, v149, v147
	v_add_f32_e32 v148, v153, v148
	v_add_f32_e32 v147, v150, v147
	v_add_f32_e32 v148, v154, v148
	v_add_f32_e32 v147, v147, v148
	ds_bpermute_b32 v148, v165, v147
	s_waitcnt lgkmcnt(0)
	v_add_f32_e32 v147, v147, v148
	ds_bpermute_b32 v148, v166, v147
	s_and_saveexec_b64 s[0:1], vcc
	s_cbranch_execz .LBB0_1925
	v_lshl_add_u32 v146, v146, 4, s2
	s_waitcnt lgkmcnt(0)
	v_add_f32_e32 v147, v147, v148
	ds_write_b32 v146, v147
.LBB0_1925:
	s_or_b64 exec, exec, s[0:1]
	v_add_u32_e32 v167, 0xb0, v164
	v_add_u32_e32 v146, s4, v167
	v_ashrrev_i32_e32 v147, 31, v146
	s_waitcnt lgkmcnt(0)
	v_lshlrev_b64 v[148:149], 12, v[146:147]
	v_lshl_add_u64 v[148:149], s[36:37], 0, v[148:149]
	v_lshl_add_u64 v[152:153], v[132:133], 1, v[148:149]
	s_nop 0
	s_waitcnt vmcnt(1)
	v_lshlrev_b32_e32 v156, 16, v216
	v_and_b32_e32 v157, 0xffff0000, v216
	v_lshlrev_b32_e32 v148, 16, v217
	v_and_b32_e32 v149, 0xffff0000, v217
	v_lshlrev_b32_e32 v158, 16, v218
	v_and_b32_e32 v159, 0xffff0000, v218
	v_lshlrev_b32_e32 v150, 16, v219
	v_and_b32_e32 v151, 0xffff0000, v219
	s_waitcnt vmcnt(0)
	v_lshlrev_b32_e32 v168, 16, v220
	v_and_b32_e32 v169, 0xffff0000, v220
	v_lshlrev_b32_e32 v152, 16, v221
	v_and_b32_e32 v153, 0xffff0000, v221
	v_lshlrev_b32_e32 v170, 16, v222
	v_and_b32_e32 v171, 0xffff0000, v222
	v_lshlrev_b32_e32 v172, 16, v223
	v_and_b32_e32 v173, 0xffff0000, v223
	v_pk_fma_f32 v[160:161], v[16:17], 0.5, v[148:149] op_sel_hi:[1,0,1]
	v_pk_fma_f32 v[162:163], v[14:15], 0.5, v[156:157] op_sel_hi:[1,0,1]
	v_pk_fma_f32 v[154:155], v[12:13], 0.5, v[150:151] op_sel_hi:[1,0,1]
	v_pk_fma_f32 v[150:151], v[8:9], 0.5, v[152:153] op_sel_hi:[1,0,1]
	v_pk_fma_f32 v[156:157], v[6:7], 0.5, v[168:169] op_sel_hi:[1,0,1]
	v_pk_fma_f32 v[158:159], v[10:11], 0.5, v[158:159] op_sel_hi:[1,0,1]
	v_pk_fma_f32 v[152:153], v[2:3], 0.5, v[170:171] op_sel_hi:[1,0,1]
	v_mul_f32_e32 v2, v163, v163
	v_mul_f32_e32 v3, v161, v161
	v_mul_f32_e32 v6, v157, v157
	v_mul_f32_e32 v7, v151, v151
	v_pk_fma_f32 v[148:149], v[4:5], 0.5, v[172:173] op_sel_hi:[1,0,1]
	v_mul_f32_e32 v4, v159, v159
	v_mul_f32_e32 v8, v153, v153
	v_fmac_f32_e32 v2, v162, v162
	v_fmac_f32_e32 v3, v160, v160
	v_fmac_f32_e32 v6, v156, v156
	v_fmac_f32_e32 v7, v150, v150
	v_mul_f32_e32 v5, v155, v155
	v_mul_f32_e32 v9, v149, v149
	v_fmac_f32_e32 v4, v158, v158
	v_fmac_f32_e32 v8, v152, v152
	v_add_f32_e32 v2, v2, v3
	v_add_f32_e32 v3, v6, v7
	v_fmac_f32_e32 v5, v154, v154
	v_fmac_f32_e32 v9, v148, v148
	v_add_f32_e32 v2, v4, v2
	v_add_f32_e32 v3, v8, v3
	v_add_f32_e32 v2, v5, v2
	v_add_f32_e32 v3, v9, v3
	v_add_f32_e32 v2, v2, v3
	ds_bpermute_b32 v3, v165, v2
	s_waitcnt lgkmcnt(0)
	v_add_f32_e32 v2, v2, v3
	ds_bpermute_b32 v3, v166, v2
	s_and_saveexec_b64 s[0:1], vcc
	s_cbranch_execz .LBB0_1927
	v_lshl_add_u32 v4, v167, 4, s2
	s_waitcnt lgkmcnt(0)
	v_add_f32_e32 v2, v2, v3
	ds_write_b32 v4, v2
